# one static s_setprio 1 for waves 0-3 at kernel entry (mirror of the waves 4-7 variant)
# speedup vs baseline: 1.0061x; 1.0061x over previous
; #define LAS __attribute__((address_space(3)))
; __global__ void __launch_bounds__(512, 2) fwd_kernel(Args a_byval) {
;     ...
;     const int tid = threadIdx.x, lane = tid & 63, wave = __builtin_amdgcn_readfirstlane(tid >> 6);
;     const int G = gridDim.x, bx = blockIdx.x;
;     const int lo = kp->ph_lo, hi = kp->ph_hi;
;     unsigned char* ws = kp->ws;
;     ...
;     volatile LAS unsigned* MISC = (volatile LAS unsigned*)(lds + RING_BYTES + 8192);
;     if (tid < 4) MISC[tid] = 0u;
_Z10fwd_kernel4Args:
	s_load_dwordx4 s[36:39], s[0:1], 0xb0
	s_load_dword s3, s[0:1], 0xc0
	s_add_u32 s4, s0, 0xc0
	v_and_b32_e32 v226, 0x3ff, v0
	v_cmp_gt_u32_e32 vcc, 4, v226
	v_readfirstlane_b32 s19, v226
	s_waitcnt lgkmcnt(0)
	v_writelane_b32 v253, s3, 0
	v_writelane_b32 v253, s0, 1
	s_addc_u32 s5, s1, 0
	s_nop 0
	v_writelane_b32 v253, s1, 2
	v_writelane_b32 v253, s4, 3
	s_nop 1
	v_writelane_b32 v253, s5, 4
	s_and_saveexec_b64 s[0:1], vcc
	v_lshl_add_u32 v1, v226, 2, 0
	v_add_u32_e32 v1, 0x22000, v1
	v_mov_b32_e32 v2, 0
	ds_write_b32 v1, v2
	s_or_b64 exec, exec, s[0:1]
	s_cmpk_ge_u32 s19, 0x100
	s_cbranch_scc1 .Lprio_done
	s_setprio 1
